# convpool unit: previous-row, next-row and conv-weight loads issued together with the current-row loads (one wait), data in registers free in this phase
# speedup vs baseline: 1.0204x; 1.0143x over previous
.LBB0_258:
	s_cmpk_gt_i32 s22, 0x23f
	s_mov_b64 s[0:1], -1
	s_cbranch_scc0 .LBB0_264
	v_mov_b32_e32 v0, v218
	s_add_i32 s36, s71, -1
	v_ashrrev_i32_e32 v30, 5, v0
	v_add_u32_e32 v40, s36, v30
	v_lshlrev_b32_e32 v0, 3, v0
	v_ashrrev_i32_e32 v41, 31, v40
	v_and_b32_e32 v32, 0xf8, v0
	v_lshlrev_b64 v[0:1], 12, v[40:41]
	v_lshl_add_u64 v[28:29], s[4:5], 0, v[0:1]
	v_lshlrev_b32_e32 v184, 1, v32
	v_lshl_add_u64 v[42:43], v[28:29], 0, v[184:185]
	global_load_dwordx4 v[8:11], v[42:43], off offset:2048
	global_load_dwordx4 v[0:3], v[42:43], off offset:2560
	global_load_dwordx4 v[4:7], v[42:43], off offset:3072
	s_add_i32 s0, s22, 0xfffffdc0
	s_cmpk_lt_u32 s0, 0x800
	s_cselect_b64 s[0:1], -1, 0
	s_and_b64 s[26:27], s[0:1], exec
	s_movk_i32 s23, 0x3800
	s_cselect_b32 s23, s23, 0x7f00
	s_and_b32 s23, s23, s36
	v_subrev_u32_e32 v31, s23, v30
	v_add_u32_e32 v45, s36, v31
	v_cmp_lt_i32_e32 vcc, 0, v45
	v_mov_b32_e32 v18, 0
	v_mov_b32_e32 v16, 0
	v_mov_b32_e32 v17, 0
	v_mov_b32_e32 v20, 0
	v_mov_b32_e32 v21, 0
	v_mov_b32_e32 v14, 0
	v_mov_b32_e32 v15, 0
	v_mov_b32_e32 v12, 0
	v_mov_b32_e32 v13, 0
	s_and_saveexec_b64 s[36:37], vcc
	s_cbranch_execz .Lcp_i1
	global_load_dwordx4 v[128:131], v[42:43], off offset:-1536
	global_load_dwordx4 v[132:135], v[42:43], off offset:-1024
.Lcp_i1:
	s_or_b64 exec, exec, s[36:37]
	s_and_b64 s[0:1], s[0:1], exec
	s_movk_i32 s0, 0x800
	s_cselect_b32 s26, s0, 0x100
	s_add_i32 s0, s26, -1
	v_cmp_gt_i32_e32 vcc, s0, v45
	s_and_saveexec_b64 s[0:1], vcc
	s_cbranch_execz .Lcp_i2
	v_lshl_add_u64 v[18:19], v[28:29], 0, v[184:185]
	v_add_co_u32_e32 v18, vcc, 0x1000, v18
	s_nop 1
	v_addc_co_u32_e32 v19, vcc, 0, v19, vcc
	global_load_dwordx4 v[136:139], v[18:19], off offset:2560
	global_load_dwordx4 v[140:143], v[18:19], off offset:3072
.Lcp_i2:
	s_or_b64 exec, exec, s[0:1]
	v_lshlrev_b32_e32 v148, 2, v32
	global_load_dwordx4 v[144:147], v148, s[28:29] offset:1024
	global_load_dwordx4 v[46:49], v148, s[28:29] offset:1040
	global_load_dwordx4 v[50:53], v148, s[28:29]
	global_load_dwordx4 v[54:57], v148, s[28:29] offset:16
	global_load_dwordx4 v[58:61], v148, s[28:29] offset:2048
	global_load_dwordx4 v[62:65], v148, s[28:29] offset:2064
	v_cmp_lt_i32_e32 vcc, 0, v45
	s_and_saveexec_b64 s[36:37], vcc
	s_cbranch_execz .Lcp_c1
	s_waitcnt vmcnt(6)
	v_lshlrev_b32_e32 v16, 16, v128
	v_and_b32_e32 v17, 0xffff0000, v128
	v_lshlrev_b32_e32 v12, 16, v129
	v_and_b32_e32 v13, 0xffff0000, v129
	v_lshlrev_b32_e32 v24, 16, v130
	v_and_b32_e32 v25, 0xffff0000, v130
	v_lshlrev_b32_e32 v26, 16, v131
	v_and_b32_e32 v27, 0xffff0000, v131
	v_lshlrev_b32_e32 v14, 16, v132
	v_and_b32_e32 v15, 0xffff0000, v132
	v_lshlrev_b32_e32 v20, 16, v133
	v_and_b32_e32 v21, 0xffff0000, v133
	v_lshlrev_b32_e32 v34, 16, v134
	v_and_b32_e32 v35, 0xffff0000, v134
	v_lshlrev_b32_e32 v22, 16, v135
	v_and_b32_e32 v23, 0xffff0000, v135
	v_pk_mul_f32 v[16:17], v[16:17], v[14:15]
	v_pk_mul_f32 v[20:21], v[12:13], v[20:21]
	v_pk_mul_f32 v[14:15], v[24:25], v[34:35]
	v_pk_mul_f32 v[12:13], v[26:27], v[22:23]
.Lcp_c1:
	s_or_b64 exec, exec, s[36:37]
	v_mov_b32_e32 v19, 0
	v_mov_b32_e32 v26, 0
	v_mov_b32_e32 v27, 0
	v_mov_b32_e32 v24, 0
	v_mov_b32_e32 v25, 0
	v_mov_b32_e32 v22, 0
	v_mov_b32_e32 v23, 0
	s_add_i32 s0, s26, -1
	v_cmp_gt_i32_e32 vcc, s0, v45
	s_and_saveexec_b64 s[0:1], vcc
	s_cbranch_execz .Lcp_c2
	s_waitcnt vmcnt(6)
	v_lshlrev_b32_e32 v18, 16, v136
	v_and_b32_e32 v19, 0xffff0000, v136
	v_lshlrev_b32_e32 v22, 16, v137
	v_and_b32_e32 v23, 0xffff0000, v137
	v_lshlrev_b32_e32 v34, 16, v138
	v_and_b32_e32 v35, 0xffff0000, v138
	v_lshlrev_b32_e32 v36, 16, v139
	v_and_b32_e32 v37, 0xffff0000, v139
	v_lshlrev_b32_e32 v24, 16, v140
	v_and_b32_e32 v25, 0xffff0000, v140
	v_lshlrev_b32_e32 v26, 16, v141
	v_and_b32_e32 v27, 0xffff0000, v141
	v_lshlrev_b32_e32 v38, 16, v142
	v_and_b32_e32 v39, 0xffff0000, v142
	v_lshlrev_b32_e32 v28, 16, v143
	v_and_b32_e32 v29, 0xffff0000, v143
	v_pk_mul_f32 v[18:19], v[18:19], v[24:25]
	v_pk_mul_f32 v[26:27], v[22:23], v[26:27]
	v_pk_mul_f32 v[24:25], v[34:35], v[38:39]
	v_pk_mul_f32 v[22:23], v[36:37], v[28:29]
.Lcp_c2:
	s_or_b64 exec, exec, s[0:1]
	v_lshrrev_b32_e32 v32, 6, v32
	s_waitcnt vmcnt(7)
	v_and_b32_e32 v39, 0xffff0000, v3
	s_waitcnt vmcnt(6)
	v_and_b32_e32 v44, 0xffff0000, v7
	v_lshlrev_b32_e64 v32, v32, 2
	v_mul_f32_e32 v39, v39, v44
	v_lshrrev_b32_e32 v44, 1, v32
	v_add_u32_e32 v30, v30, v32
	v_sub_u32_e32 v31, v31, v44
	v_subrev_u32_e32 v30, s23, v30
	v_add_u32_e32 v74, s71, v31
	v_sub_u32_e32 v30, v30, v44
	v_add_u32_e32 v75, -1, v74
	v_add3_u32 v30, s71, v30, -1
	v_min_i32_e32 v76, s26, v30
	v_max_i32_e32 v30, 0, v75
	v_sub_u32_e32 v30, v76, v30
	v_cvt_f32_i32_e32 v30, v30
	v_and_b32_e32 v68, 0xffff0000, v4
	v_lshlrev_b32_e32 v4, 16, v4
	v_and_b32_e32 v71, 0xffff0000, v0
	v_div_scale_f32 v31, s[0:1], v30, v30, 1.0
	v_rcp_f32_e32 v32, v31
	v_lshlrev_b32_e32 v0, 16, v0
	v_mul_f32_e32 v0, v0, v4
	v_div_scale_f32 v4, vcc, 1.0, v30, 1.0
	v_fma_f32 v44, -v31, v32, 1.0
	v_fmac_f32_e32 v32, v44, v32
	v_lshlrev_b32_e32 v7, 16, v7
	v_and_b32_e32 v66, 0xffff0000, v6
	v_lshlrev_b32_e32 v3, 16, v3
	v_and_b32_e32 v69, 0xffff0000, v2
	v_mul_f32_e32 v44, v4, v32
	v_mul_f32_e32 v3, v3, v7
	v_mul_f32_e32 v7, v69, v66
	v_fma_f32 v66, -v31, v44, v4
	v_fmac_f32_e32 v44, v66, v32
	v_lshlrev_b32_e32 v6, 16, v6
	v_and_b32_e32 v67, 0xffff0000, v5
	v_lshlrev_b32_e32 v5, 16, v5
	v_lshlrev_b32_e32 v2, 16, v2
	v_and_b32_e32 v70, 0xffff0000, v1
	v_lshlrev_b32_e32 v1, 16, v1
	v_fma_f32 v4, -v31, v44, v4
	v_mul_f32_e32 v2, v2, v6
	v_mul_f32_e32 v6, v70, v67
	v_mul_f32_e32 v1, v1, v5
	v_mul_f32_e32 v5, v71, v68
	v_div_fmas_f32 v4, v4, v32, v44
	v_div_fixup_f32 v44, v4, v30, 1.0
	s_lshl_b32 s0, s23, 12
	v_lshlrev_b32_e32 v28, 16, v8
	v_and_b32_e32 v8, 0xffff0000, v8
	v_lshlrev_b32_e32 v29, 16, v9
	v_and_b32_e32 v9, 0xffff0000, v9
	s_add_u32 s0, s4, s0
	s_addc_u32 s1, s5, 0
	v_lshlrev_b32_e32 v33, 16, v10
	v_and_b32_e32 v10, 0xffff0000, v10
	v_cmp_lt_i32_e32 vcc, -1, v75
	v_lshlrev_b32_e32 v38, 16, v11
	v_and_b32_e32 v11, 0xffff0000, v11
	v_readlane_b32 s4, v253, 16
	v_readlane_b32 s8, v253, 20
	v_readlane_b32 s9, v253, 21
	v_readlane_b32 s5, v253, 17
	s_nop 1
	s_waitcnt vmcnt(5)
	v_mul_f32_e32 v0, v0, v144
	v_mul_f32_e32 v4, v5, v145
	v_mul_f32_e32 v1, v1, v146
	v_mul_f32_e32 v5, v6, v147
	s_waitcnt vmcnt(3)
	v_fmac_f32_e32 v0, v16, v50
	v_fmac_f32_e32 v4, v17, v51
	v_fmac_f32_e32 v1, v20, v52
	v_fmac_f32_e32 v5, v21, v53
	v_mul_f32_e32 v2, v2, v46
	s_waitcnt vmcnt(1)
	v_fmac_f32_e32 v0, v18, v58
	v_fmac_f32_e32 v4, v19, v59
	v_fmac_f32_e32 v1, v26, v60
	v_fmac_f32_e32 v5, v27, v61
	v_mul_f32_e32 v6, v7, v47
	v_fmac_f32_e32 v2, v14, v54
	v_mul_f32_e32 v0, v0, v28
	v_mul_f32_e32 v4, v4, v8
	v_mul_f32_e32 v1, v1, v29
	v_mul_f32_e32 v5, v5, v9
	v_fmac_f32_e32 v6, v15, v55
	v_mul_f32_e32 v3, v3, v48
	v_mul_f32_e32 v7, v39, v49
	s_waitcnt vmcnt(0)
	v_fmac_f32_e32 v2, v24, v62
	v_fmac_f32_e32 v6, v25, v63
	v_fmac_f32_e32 v3, v12, v56
	v_fmac_f32_e32 v7, v13, v57
	v_cvt_pk_bf16_f32 v0, v0, v4
	v_cvt_pk_bf16_f32 v1, v1, v5
	v_lshl_add_u64 v[4:5], s[0:1], 0, v[184:185]
	v_cmp_gt_i32_e64 s[0:1], s26, v75
	v_mul_f32_e32 v2, v2, v33
	v_mul_f32_e32 v6, v6, v10
	v_fmac_f32_e32 v3, v22, v64
	v_fmac_f32_e32 v7, v23, v65
	s_and_b64 s[64:65], vcc, s[0:1]
	v_cmp_lt_i32_e32 vcc, -2, v75
	v_cmp_lt_i32_e64 s[0:1], v74, v76
	v_mul_f32_e32 v3, v3, v38
	v_mul_f32_e32 v7, v7, v11
	v_cvt_pk_bf16_f32 v2, v2, v6
	v_cndmask_b32_e64 v6, v45, v75, s[64:65]
	s_and_b64 s[62:63], vcc, s[0:1]
	v_cvt_pk_bf16_f32 v3, v3, v7
	v_ashrrev_i32_e32 v7, 31, v6
	v_cndmask_b32_e64 v8, v45, v74, s[62:63]
	v_lshlrev_b64 v[6:7], 12, v[6:7]
	v_ashrrev_i32_e32 v9, 31, v8
	v_lshl_add_u64 v[6:7], v[4:5], 0, v[6:7]
	v_lshlrev_b64 v[8:9], 12, v[8:9]
	v_lshl_add_u64 v[8:9], v[4:5], 0, v[8:9]
	global_load_dwordx4 v[46:49], v[6:7], off offset:3584
	global_load_dwordx4 v[50:53], v[8:9], off offset:3584
	v_add_u32_e32 v6, 1, v74
	v_cmp_lt_i32_e32 vcc, -3, v75
	v_cmp_lt_i32_e64 s[0:1], v6, v76
	v_add_u32_e32 v8, 2, v74
	s_and_b64 s[60:61], vcc, s[0:1]
	v_cmp_lt_i32_e32 vcc, -4, v75
	v_cmp_lt_i32_e64 s[0:1], v8, v76
	v_cndmask_b32_e64 v6, v45, v6, s[60:61]
	s_and_b64 s[58:59], vcc, s[0:1]
	v_ashrrev_i32_e32 v7, 31, v6
	v_cndmask_b32_e64 v8, v45, v8, s[58:59]
	v_lshlrev_b64 v[6:7], 12, v[6:7]
	v_ashrrev_i32_e32 v9, 31, v8
	v_lshl_add_u64 v[6:7], v[4:5], 0, v[6:7]
	v_lshlrev_b64 v[8:9], 12, v[8:9]
	v_lshl_add_u64 v[8:9], v[4:5], 0, v[8:9]
	global_load_dwordx4 v[54:57], v[6:7], off offset:3584
	global_load_dwordx4 v[58:61], v[8:9], off offset:3584
	v_add_u32_e32 v6, 3, v74
	v_cmp_lt_i32_e32 vcc, -5, v75
	v_cmp_lt_i32_e64 s[0:1], v6, v76
	v_add_u32_e32 v8, 4, v74
	s_and_b64 s[0:1], vcc, s[0:1]
	v_cmp_lt_i32_e32 vcc, -6, v75
	v_cmp_lt_i32_e64 s[36:37], v8, v76
	v_cndmask_b32_e64 v6, v45, v6, s[0:1]
	s_and_b64 s[54:55], vcc, s[36:37]
	v_ashrrev_i32_e32 v7, 31, v6
	v_cndmask_b32_e64 v8, v45, v8, s[54:55]
	v_lshlrev_b64 v[6:7], 12, v[6:7]
	v_ashrrev_i32_e32 v9, 31, v8
	v_lshl_add_u64 v[6:7], v[4:5], 0, v[6:7]
	v_lshlrev_b64 v[8:9], 12, v[8:9]
	v_lshl_add_u64 v[8:9], v[4:5], 0, v[8:9]
	global_load_dwordx4 v[62:65], v[6:7], off offset:3584
	global_load_dwordx4 v[66:69], v[8:9], off offset:3584
	v_add_u32_e32 v6, 5, v74
	v_cmp_lt_i32_e32 vcc, -7, v75
	v_cmp_lt_i32_e64 s[36:37], v6, v76
	v_add_u32_e32 v8, 6, v74
	s_and_b64 s[52:53], vcc, s[36:37]
	v_cmp_lt_i32_e32 vcc, -8, v75
	v_cmp_lt_i32_e64 s[36:37], v8, v76
	v_cndmask_b32_e64 v6, v45, v6, s[52:53]
	s_and_b64 s[50:51], vcc, s[36:37]
	v_ashrrev_i32_e32 v7, 31, v6
	v_cndmask_b32_e64 v8, v45, v8, s[50:51]
	v_lshlrev_b64 v[6:7], 12, v[6:7]
	v_ashrrev_i32_e32 v9, 31, v8
	v_lshl_add_u64 v[6:7], v[4:5], 0, v[6:7]
	v_lshlrev_b64 v[8:9], 12, v[8:9]
	v_lshl_add_u64 v[8:9], v[4:5], 0, v[8:9]
	global_load_dwordx4 v[70:73], v[6:7], off offset:3584
	global_load_dwordx4 v[36:39], v[8:9], off offset:3584
	v_add_u32_e32 v6, 7, v74
	v_cmp_lt_i32_e32 vcc, -9, v75
	v_cmp_lt_i32_e64 s[36:37], v6, v76
	v_add_u32_e32 v8, 8, v74
	s_and_b64 s[48:49], vcc, s[36:37]
	v_cmp_lt_i32_e32 vcc, -10, v75
	v_cmp_lt_i32_e64 s[36:37], v8, v76
	v_cndmask_b32_e64 v6, v45, v6, s[48:49]
	s_and_b64 s[46:47], vcc, s[36:37]
	v_ashrrev_i32_e32 v7, 31, v6
	v_cndmask_b32_e64 v8, v45, v8, s[46:47]
	v_lshlrev_b64 v[6:7], 12, v[6:7]
	v_ashrrev_i32_e32 v9, 31, v8
	v_lshl_add_u64 v[6:7], v[4:5], 0, v[6:7]
	v_lshlrev_b64 v[8:9], 12, v[8:9]
	v_lshl_add_u64 v[8:9], v[4:5], 0, v[8:9]
	global_load_dwordx4 v[32:35], v[6:7], off offset:3584
	global_load_dwordx4 v[28:31], v[8:9], off offset:3584
	v_add_u32_e32 v6, 9, v74
	v_cmp_lt_i32_e32 vcc, -11, v75
	v_cmp_lt_i32_e64 s[36:37], v6, v76
	v_add_u32_e32 v8, 10, v74
	s_and_b64 s[44:45], vcc, s[36:37]
	v_cmp_lt_i32_e32 vcc, -12, v75
	v_cmp_lt_i32_e64 s[36:37], v8, v76
	v_cndmask_b32_e64 v6, v45, v6, s[44:45]
	s_and_b64 s[42:43], vcc, s[36:37]
	v_ashrrev_i32_e32 v7, 31, v6
	v_cndmask_b32_e64 v8, v45, v8, s[42:43]
	v_lshlrev_b64 v[6:7], 12, v[6:7]
	v_ashrrev_i32_e32 v9, 31, v8
	v_lshl_add_u64 v[6:7], v[4:5], 0, v[6:7]
	v_lshlrev_b64 v[8:9], 12, v[8:9]
	v_lshl_add_u64 v[8:9], v[4:5], 0, v[8:9]
	global_load_dwordx4 v[24:27], v[6:7], off offset:3584
	global_load_dwordx4 v[20:23], v[8:9], off offset:3584
	v_add_u32_e32 v6, 11, v74
	v_cmp_lt_i32_e32 vcc, -13, v75
	v_cmp_lt_i32_e64 s[36:37], v6, v76
	v_add_u32_e32 v8, 12, v74
	s_and_b64 s[40:41], vcc, s[36:37]
	v_cmp_lt_i32_e32 vcc, -14, v75
	v_cmp_lt_i32_e64 s[36:37], v8, v76
	v_cndmask_b32_e64 v6, v45, v6, s[40:41]
	s_and_b64 s[38:39], vcc, s[36:37]
	v_ashrrev_i32_e32 v7, 31, v6
	v_cndmask_b32_e64 v8, v45, v8, s[38:39]
	v_lshlrev_b64 v[6:7], 12, v[6:7]
	v_ashrrev_i32_e32 v9, 31, v8
	v_lshl_add_u64 v[6:7], v[4:5], 0, v[6:7]
	v_lshlrev_b64 v[8:9], 12, v[8:9]
	v_lshl_add_u64 v[8:9], v[4:5], 0, v[8:9]
	global_load_dwordx4 v[16:19], v[6:7], off offset:3584
	global_load_dwordx4 v[12:15], v[8:9], off offset:3584
	v_add_u32_e32 v6, 13, v74
	v_cmp_lt_i32_e32 vcc, -15, v75
	v_cmp_lt_i32_e64 s[36:37], v6, v76
	v_add_u32_e32 v8, 14, v74
	s_and_b64 s[36:37], vcc, s[36:37]
	v_cmp_lt_i32_e32 vcc, -16, v75
	v_cmp_lt_i32_e64 s[68:69], v8, v76
	s_and_b64 vcc, vcc, s[68:69]
	s_waitcnt vmcnt(13)
	v_lshlrev_b32_e32 v76, 16, v49
	v_and_b32_e32 v49, 0xffff0000, v49
	v_cndmask_b32_e64 v6, v45, v6, s[36:37]
	v_cndmask_b32_e32 v8, v45, v8, vcc
	v_lshlrev_b32_e32 v45, 16, v46
	v_and_b32_e32 v46, 0xffff0000, v46
	v_add_f32_e32 v49, 0, v49
	s_waitcnt vmcnt(12)
	v_lshlrev_b32_e32 v80, 16, v53
	v_and_b32_e32 v53, 0xffff0000, v53
	v_lshlrev_b32_e32 v74, 16, v47
	v_add_f32_e32 v45, 0, v45
	v_add_f32_e32 v46, 0, v46
	v_cndmask_b32_e64 v49, 0, v49, s[64:65]
	v_lshlrev_b32_e32 v77, 16, v50
	v_and_b32_e32 v50, 0xffff0000, v50
	v_cndmask_b32_e64 v53, 0, v53, s[62:63]
	v_and_b32_e32 v47, 0xffff0000, v47
	v_cndmask_b32_e64 v45, 0, v45, s[64:65]
	v_cndmask_b32_e64 v46, 0, v46, s[64:65]
	v_add_f32_e32 v74, 0, v74
	v_lshlrev_b32_e32 v78, 16, v51
	v_cndmask_b32_e64 v77, 0, v77, s[62:63]
	v_cndmask_b32_e64 v50, 0, v50, s[62:63]
	v_add_f32_e32 v49, v49, v53
	s_waitcnt vmcnt(11)
	v_lshlrev_b32_e32 v53, 16, v54
	v_lshlrev_b32_e32 v75, 16, v48
	v_cndmask_b32_e64 v74, 0, v74, s[64:65]
	v_add_f32_e32 v47, 0, v47
	v_and_b32_e32 v51, 0xffff0000, v51
	v_add_f32_e32 v45, v45, v77
	v_add_f32_e32 v46, v46, v50
	v_cndmask_b32_e64 v50, 0, v78, s[62:63]
	v_and_b32_e32 v54, 0xffff0000, v54
	v_cndmask_b32_e64 v53, 0, v53, s[60:61]
	v_and_b32_e32 v48, 0xffff0000, v48
	v_cndmask_b32_e64 v47, 0, v47, s[64:65]
	v_add_f32_e32 v75, 0, v75
	v_lshlrev_b32_e32 v79, 16, v52
	v_add_f32_e32 v50, v74, v50
	v_cndmask_b32_e64 v51, 0, v51, s[62:63]
	v_lshlrev_b32_e32 v74, 16, v55
	v_add_f32_e32 v45, v45, v53
	v_cndmask_b32_e64 v53, 0, v54, s[60:61]
	v_cndmask_b32_e64 v75, 0, v75, s[64:65]
	v_add_f32_e32 v48, 0, v48
	v_and_b32_e32 v52, 0xffff0000, v52
	v_add_f32_e32 v47, v47, v51
	v_cndmask_b32_e64 v51, 0, v79, s[62:63]
	v_and_b32_e32 v55, 0xffff0000, v55
	v_add_f32_e32 v46, v46, v53
	v_cndmask_b32_e64 v53, 0, v74, s[60:61]
	v_cndmask_b32_e64 v48, 0, v48, s[64:65]
	v_add_f32_e32 v76, 0, v76
	v_add_f32_e32 v51, v75, v51
	v_cndmask_b32_e64 v52, 0, v52, s[62:63]
	v_lshlrev_b32_e32 v75, 16, v56
	v_add_f32_e32 v50, v50, v53
	v_cndmask_b32_e64 v53, 0, v55, s[60:61]
	v_cndmask_b32_e64 v76, 0, v76, s[64:65]
	v_add_f32_e32 v48, v48, v52
	v_cndmask_b32_e64 v52, 0, v80, s[62:63]
	v_and_b32_e32 v56, 0xffff0000, v56
	v_add_f32_e32 v47, v47, v53
	v_cndmask_b32_e64 v53, 0, v75, s[60:61]
	v_add_f32_e32 v52, v76, v52
	v_lshlrev_b32_e32 v76, 16, v57
	v_add_f32_e32 v51, v51, v53
	v_cndmask_b32_e64 v53, 0, v56, s[60:61]
	v_and_b32_e32 v57, 0xffff0000, v57
	v_add_f32_e32 v48, v48, v53
	v_cndmask_b32_e64 v53, 0, v76, s[60:61]
	v_add_f32_e32 v52, v52, v53
	v_cndmask_b32_e64 v53, 0, v57, s[60:61]
	v_add_f32_e32 v49, v49, v53
	s_waitcnt vmcnt(10)
	v_lshlrev_b32_e32 v53, 16, v58
	v_and_b32_e32 v54, 0xffff0000, v58
	v_cndmask_b32_e64 v53, 0, v53, s[58:59]
	v_lshlrev_b32_e32 v55, 16, v59
	v_add_f32_e32 v45, v45, v53
	v_cndmask_b32_e64 v53, 0, v54, s[58:59]
	v_and_b32_e32 v56, 0xffff0000, v59
	v_add_f32_e32 v46, v46, v53
	v_cndmask_b32_e64 v53, 0, v55, s[58:59]
	v_lshlrev_b32_e32 v57, 16, v60
	v_add_f32_e32 v50, v50, v53
	v_cndmask_b32_e64 v53, 0, v56, s[58:59]
	v_and_b32_e32 v58, 0xffff0000, v60
	v_add_f32_e32 v47, v47, v53
	v_cndmask_b32_e64 v53, 0, v57, s[58:59]
	v_lshlrev_b32_e32 v59, 16, v61
	v_add_f32_e32 v51, v51, v53
	v_cndmask_b32_e64 v53, 0, v58, s[58:59]
	v_and_b32_e32 v60, 0xffff0000, v61
	v_add_f32_e32 v48, v48, v53
	v_cndmask_b32_e64 v53, 0, v59, s[58:59]
	v_add_f32_e32 v52, v52, v53
	v_cndmask_b32_e64 v53, 0, v60, s[58:59]
	v_add_f32_e32 v49, v49, v53
	s_waitcnt vmcnt(9)
	v_lshlrev_b32_e32 v53, 16, v62
	v_and_b32_e32 v54, 0xffff0000, v62
	v_cndmask_b32_e64 v53, 0, v53, s[0:1]
	v_lshlrev_b32_e32 v55, 16, v63
	v_add_f32_e32 v45, v45, v53
	v_cndmask_b32_e64 v53, 0, v54, s[0:1]
	v_and_b32_e32 v56, 0xffff0000, v63
	v_add_f32_e32 v46, v46, v53
	v_cndmask_b32_e64 v53, 0, v55, s[0:1]
	v_lshlrev_b32_e32 v57, 16, v64
	v_add_f32_e32 v50, v50, v53
	v_cndmask_b32_e64 v53, 0, v56, s[0:1]
	v_and_b32_e32 v58, 0xffff0000, v64
	v_add_f32_e32 v47, v47, v53
	v_cndmask_b32_e64 v53, 0, v57, s[0:1]
	v_lshlrev_b32_e32 v59, 16, v65
	v_add_f32_e32 v51, v51, v53
	v_cndmask_b32_e64 v53, 0, v58, s[0:1]
	v_and_b32_e32 v60, 0xffff0000, v65
	v_add_f32_e32 v48, v48, v53
	v_cndmask_b32_e64 v53, 0, v59, s[0:1]
	v_add_f32_e32 v52, v52, v53
	v_cndmask_b32_e64 v53, 0, v60, s[0:1]
	v_add_f32_e32 v49, v49, v53
	s_waitcnt vmcnt(8)
	v_lshlrev_b32_e32 v53, 16, v66
	v_and_b32_e32 v54, 0xffff0000, v66
	v_cndmask_b32_e64 v53, 0, v53, s[54:55]
	v_lshlrev_b32_e32 v55, 16, v67
	v_add_f32_e32 v45, v45, v53
	v_cndmask_b32_e64 v53, 0, v54, s[54:55]
	v_and_b32_e32 v56, 0xffff0000, v67
	v_add_f32_e32 v46, v46, v53
	v_cndmask_b32_e64 v53, 0, v55, s[54:55]
	v_lshlrev_b32_e32 v57, 16, v68
	v_add_f32_e32 v50, v50, v53
	v_cndmask_b32_e64 v53, 0, v56, s[54:55]
	v_and_b32_e32 v58, 0xffff0000, v68
	v_add_f32_e32 v47, v47, v53
	v_cndmask_b32_e64 v53, 0, v57, s[54:55]
	v_lshlrev_b32_e32 v59, 16, v69
	v_add_f32_e32 v51, v51, v53
	v_cndmask_b32_e64 v53, 0, v58, s[54:55]
	v_and_b32_e32 v60, 0xffff0000, v69
	v_add_f32_e32 v48, v48, v53
	v_cndmask_b32_e64 v53, 0, v59, s[54:55]
	v_add_f32_e32 v52, v52, v53
	v_cndmask_b32_e64 v53, 0, v60, s[54:55]
	v_add_f32_e32 v49, v49, v53
	s_waitcnt vmcnt(7)
	v_lshlrev_b32_e32 v53, 16, v70
	v_and_b32_e32 v54, 0xffff0000, v70
	v_cndmask_b32_e64 v53, 0, v53, s[52:53]
	v_lshlrev_b32_e32 v55, 16, v71
	v_add_f32_e32 v45, v45, v53
	v_cndmask_b32_e64 v53, 0, v54, s[52:53]
	v_and_b32_e32 v56, 0xffff0000, v71
	v_add_f32_e32 v46, v46, v53
	v_cndmask_b32_e64 v53, 0, v55, s[52:53]
	v_lshlrev_b32_e32 v57, 16, v72
	v_add_f32_e32 v50, v50, v53
	v_cndmask_b32_e64 v53, 0, v56, s[52:53]
	v_and_b32_e32 v58, 0xffff0000, v72
	v_add_f32_e32 v47, v47, v53
	v_cndmask_b32_e64 v53, 0, v57, s[52:53]
	v_lshlrev_b32_e32 v59, 16, v73
	v_add_f32_e32 v51, v51, v53
	v_cndmask_b32_e64 v53, 0, v58, s[52:53]
	v_and_b32_e32 v60, 0xffff0000, v73
	v_add_f32_e32 v48, v48, v53
	v_cndmask_b32_e64 v53, 0, v59, s[52:53]
	v_add_f32_e32 v52, v52, v53
	v_cndmask_b32_e64 v53, 0, v60, s[52:53]
	v_add_f32_e32 v49, v49, v53
	s_waitcnt vmcnt(6)
	v_lshlrev_b32_e32 v53, 16, v36
	v_and_b32_e32 v36, 0xffff0000, v36
	v_lshlrev_b32_e32 v56, 16, v39
	v_and_b32_e32 v39, 0xffff0000, v39
	v_lshlrev_b32_e32 v54, 16, v37
	v_and_b32_e32 v37, 0xffff0000, v37
	v_cndmask_b32_e64 v36, 0, v36, s[50:51]
	v_cndmask_b32_e64 v39, 0, v39, s[50:51]
	v_lshlrev_b32_e32 v55, 16, v38
	v_and_b32_e32 v38, 0xffff0000, v38
	v_add_f32_e32 v36, v46, v36
	v_cndmask_b32_e64 v46, 0, v54, s[50:51]
	v_cndmask_b32_e64 v37, 0, v37, s[50:51]
	v_add_f32_e32 v39, v49, v39
	s_waitcnt vmcnt(5)
	v_lshlrev_b32_e32 v49, 16, v32
	v_and_b32_e32 v32, 0xffff0000, v32
	v_add_f32_e32 v46, v50, v46
	v_add_f32_e32 v37, v47, v37
	v_cndmask_b32_e64 v47, 0, v55, s[50:51]
	v_cndmask_b32_e64 v38, 0, v38, s[50:51]
	v_lshlrev_b32_e32 v50, 16, v33
	v_and_b32_e32 v33, 0xffff0000, v33
	v_cndmask_b32_e64 v32, 0, v32, s[48:49]
	v_add_f32_e32 v47, v51, v47
	v_add_f32_e32 v38, v48, v38
	v_cndmask_b32_e64 v48, 0, v56, s[50:51]
	v_lshlrev_b32_e32 v51, 16, v34
	v_and_b32_e32 v34, 0xffff0000, v34
	v_add_f32_e32 v32, v36, v32
	v_cndmask_b32_e64 v36, 0, v50, s[48:49]
	v_cndmask_b32_e64 v33, 0, v33, s[48:49]
	v_add_f32_e32 v48, v52, v48
	v_lshlrev_b32_e32 v52, 16, v35
	v_and_b32_e32 v35, 0xffff0000, v35
	v_add_f32_e32 v36, v46, v36
	v_add_f32_e32 v33, v37, v33
	v_cndmask_b32_e64 v37, 0, v51, s[48:49]
	v_cndmask_b32_e64 v34, 0, v34, s[48:49]
	s_waitcnt vmcnt(4)
	v_lshlrev_b32_e32 v46, 16, v29
	v_and_b32_e32 v29, 0xffff0000, v29
	v_add_f32_e32 v37, v47, v37
	v_add_f32_e32 v34, v38, v34
	v_cndmask_b32_e64 v38, 0, v52, s[48:49]
	v_cndmask_b32_e64 v35, 0, v35, s[48:49]
	v_lshlrev_b32_e32 v47, 16, v30
	v_and_b32_e32 v30, 0xffff0000, v30
	v_cndmask_b32_e64 v29, 0, v29, s[46:47]
	v_add_f32_e32 v38, v48, v38
	v_add_f32_e32 v35, v39, v35
	v_lshlrev_b32_e32 v39, 16, v28
	v_and_b32_e32 v28, 0xffff0000, v28
	v_lshlrev_b32_e32 v48, 16, v31
	v_and_b32_e32 v31, 0xffff0000, v31
	v_add_f32_e32 v29, v33, v29
	v_cndmask_b32_e64 v33, 0, v47, s[46:47]
	v_cndmask_b32_e64 v30, 0, v30, s[46:47]
	v_cndmask_b32_e64 v28, 0, v28, s[46:47]
	v_add_f32_e32 v33, v37, v33
	v_add_f32_e32 v30, v34, v30
	v_cndmask_b32_e64 v34, 0, v48, s[46:47]
	v_cndmask_b32_e64 v31, 0, v31, s[46:47]
	s_waitcnt vmcnt(3)
	v_lshlrev_b32_e32 v37, 16, v26
	v_and_b32_e32 v26, 0xffff0000, v26
	v_ashrrev_i32_e32 v7, 31, v6
	v_ashrrev_i32_e32 v9, 31, v8
	v_add_f32_e32 v28, v32, v28
	v_cndmask_b32_e64 v32, 0, v46, s[46:47]
	v_add_f32_e32 v34, v38, v34
	v_add_f32_e32 v31, v35, v31
	v_lshlrev_b32_e32 v35, 16, v24
	v_and_b32_e32 v24, 0xffff0000, v24
	v_lshlrev_b32_e32 v38, 16, v27
	v_and_b32_e32 v27, 0xffff0000, v27
	v_cndmask_b32_e64 v26, 0, v26, s[44:45]
	v_lshlrev_b64 v[6:7], 12, v[6:7]
	v_lshlrev_b64 v[8:9], 12, v[8:9]
	v_add_f32_e32 v32, v36, v32
	v_lshlrev_b32_e32 v36, 16, v25
	v_and_b32_e32 v25, 0xffff0000, v25
	v_cndmask_b32_e64 v24, 0, v24, s[44:45]
	v_add_f32_e32 v26, v30, v26
	v_cndmask_b32_e64 v30, 0, v38, s[44:45]
	v_cndmask_b32_e64 v27, 0, v27, s[44:45]
	v_lshl_add_u64 v[6:7], v[4:5], 0, v[6:7]
	v_lshl_add_u64 v[4:5], v[4:5], 0, v[8:9]
	v_cndmask_b32_e64 v53, 0, v53, s[50:51]
	v_add_f32_e32 v24, v28, v24
	v_cndmask_b32_e64 v28, 0, v36, s[44:45]
	v_cndmask_b32_e64 v25, 0, v25, s[44:45]
	v_add_f32_e32 v30, v34, v30
	v_add_f32_e32 v27, v31, v27
	s_waitcnt vmcnt(2)
	v_lshlrev_b32_e32 v31, 16, v20
	v_and_b32_e32 v20, 0xffff0000, v20
	v_lshlrev_b32_e32 v34, 16, v23
	v_and_b32_e32 v23, 0xffff0000, v23
	global_load_dwordx4 v[8:11], v[6:7], off offset:3584
	s_nop 0
	global_load_dwordx4 v[4:7], v[4:5], off offset:3584
	v_add_f32_e32 v45, v45, v53
	v_cndmask_b32_e64 v49, 0, v49, s[48:49]
	v_add_f32_e32 v28, v32, v28
	v_add_f32_e32 v25, v29, v25
	v_cndmask_b32_e64 v29, 0, v37, s[44:45]
	v_lshlrev_b32_e32 v32, 16, v21
	v_cndmask_b32_e64 v20, 0, v20, s[42:43]
	v_cndmask_b32_e64 v23, 0, v23, s[42:43]
	v_add_f32_e32 v45, v45, v49
	v_cndmask_b32_e64 v39, 0, v39, s[46:47]
	v_add_f32_e32 v29, v33, v29
	v_and_b32_e32 v21, 0xffff0000, v21
	v_lshlrev_b32_e32 v33, 16, v22
	v_and_b32_e32 v22, 0xffff0000, v22
	v_add_f32_e32 v20, v24, v20
	v_cndmask_b32_e64 v24, 0, v32, s[42:43]
	v_add_f32_e32 v23, v27, v23
	s_waitcnt vmcnt(3)
	v_lshlrev_b32_e32 v27, 16, v16
	v_and_b32_e32 v16, 0xffff0000, v16
	v_add_f32_e32 v39, v45, v39
	v_cndmask_b32_e64 v35, 0, v35, s[44:45]
	v_add_f32_e32 v24, v28, v24
	v_cndmask_b32_e64 v21, 0, v21, s[42:43]
	v_cndmask_b32_e64 v22, 0, v22, s[42:43]
	v_lshlrev_b32_e32 v28, 16, v17
	v_cndmask_b32_e64 v16, 0, v16, s[40:41]
	v_add_f32_e32 v35, v39, v35
	v_cndmask_b32_e64 v31, 0, v31, s[42:43]
	v_add_f32_e32 v21, v25, v21
	v_cndmask_b32_e64 v25, 0, v33, s[42:43]
	v_add_f32_e32 v22, v26, v22
	v_cndmask_b32_e64 v26, 0, v34, s[42:43]
	v_and_b32_e32 v17, 0xffff0000, v17
	v_add_f32_e32 v20, v20, v16
	v_cndmask_b32_e64 v16, 0, v28, s[40:41]
	v_add_f32_e32 v31, v35, v31
	v_add_f32_e32 v25, v29, v25
	v_add_f32_e32 v26, v30, v26
	v_lshlrev_b32_e32 v29, 16, v18
	v_and_b32_e32 v30, 0xffff0000, v18
	v_cndmask_b32_e64 v18, 0, v27, s[40:41]
	v_add_f32_e32 v24, v24, v16
	v_cndmask_b32_e64 v16, 0, v17, s[40:41]
	v_lshlrev_b32_e32 v32, 16, v19
	v_and_b32_e32 v33, 0xffff0000, v19
	v_add_f32_e32 v27, v31, v18
	v_add_f32_e32 v21, v21, v16
	global_load_dwordx4 v[16:19], v[42:43], off offset:3584
	v_cndmask_b32_e64 v28, 0, v29, s[40:41]
	v_add_f32_e32 v25, v25, v28
	v_cndmask_b32_e64 v28, 0, v30, s[40:41]
	v_add_f32_e32 v22, v22, v28
	v_cndmask_b32_e64 v28, 0, v32, s[40:41]
	v_add_f32_e32 v26, v26, v28
	v_cndmask_b32_e64 v28, 0, v33, s[40:41]
	v_add_f32_e32 v23, v23, v28
	s_waitcnt vmcnt(3)
	v_lshlrev_b32_e32 v28, 16, v12
	v_and_b32_e32 v12, 0xffff0000, v12
	v_lshlrev_b32_e32 v29, 16, v13
	v_and_b32_e32 v13, 0xffff0000, v13
	v_lshlrev_b32_e32 v30, 16, v14
	v_and_b32_e32 v14, 0xffff0000, v14
	v_lshlrev_b32_e32 v31, 16, v15
	v_and_b32_e32 v15, 0xffff0000, v15
	v_cndmask_b32_e64 v12, 0, v12, s[38:39]
	v_add_f32_e32 v12, v20, v12
	v_cndmask_b32_e64 v20, 0, v29, s[38:39]
	v_cndmask_b32_e64 v13, 0, v13, s[38:39]
	v_cndmask_b32_e64 v14, 0, v14, s[38:39]
	v_cndmask_b32_e64 v15, 0, v15, s[38:39]
	v_add_f32_e32 v20, v24, v20
	v_add_f32_e32 v13, v21, v13
	v_cndmask_b32_e64 v21, 0, v30, s[38:39]
	v_add_f32_e32 v14, v22, v14
	v_cndmask_b32_e64 v22, 0, v31, s[38:39]
	v_add_f32_e32 v15, v23, v15
	v_add_f32_e32 v21, v25, v21
	v_add_f32_e32 v22, v26, v22
	s_waitcnt vmcnt(2)
	v_lshlrev_b32_e32 v23, 16, v8
	v_and_b32_e32 v8, 0xffff0000, v8
	v_lshlrev_b32_e32 v24, 16, v9
	v_and_b32_e32 v9, 0xffff0000, v9
	v_lshlrev_b32_e32 v25, 16, v10
	v_and_b32_e32 v10, 0xffff0000, v10
	v_lshlrev_b32_e32 v26, 16, v11
	v_and_b32_e32 v11, 0xffff0000, v11
	v_cndmask_b32_e64 v8, 0, v8, s[36:37]
	v_cndmask_b32_e64 v9, 0, v9, s[36:37]
	v_add_f32_e32 v8, v12, v8
	v_cndmask_b32_e64 v12, 0, v24, s[36:37]
	v_add_f32_e32 v9, v13, v9
	v_cndmask_b32_e64 v13, 0, v25, s[36:37]
	v_cndmask_b32_e64 v10, 0, v10, s[36:37]
	v_cndmask_b32_e64 v11, 0, v11, s[36:37]
	v_add_f32_e32 v12, v20, v12
	v_add_f32_e32 v13, v21, v13
	v_add_f32_e32 v10, v14, v10
	v_cndmask_b32_e64 v14, 0, v26, s[36:37]
	v_add_f32_e32 v11, v15, v11
	s_waitcnt vmcnt(1)
	v_lshlrev_b32_e32 v15, 16, v4
	v_and_b32_e32 v4, 0xffff0000, v4
	v_lshlrev_b32_e32 v20, 16, v5
	v_and_b32_e32 v5, 0xffff0000, v5
	v_lshlrev_b32_e32 v21, 16, v6
	v_and_b32_e32 v6, 0xffff0000, v6
	v_add_f32_e32 v14, v22, v14
	v_lshlrev_b32_e32 v22, 16, v7
	v_cndmask_b32_e32 v4, 0, v4, vcc
	v_cndmask_b32_e32 v5, 0, v5, vcc
	v_cndmask_b32_e32 v6, 0, v6, vcc
	v_add_f32_e32 v4, v8, v4
	v_cndmask_b32_e32 v8, 0, v20, vcc
	v_add_f32_e32 v5, v9, v5
	v_cndmask_b32_e32 v9, 0, v21, vcc
	v_add_f32_e32 v6, v10, v6
	v_cndmask_b32_e32 v10, 0, v22, vcc
	v_cndmask_b32_e64 v28, 0, v28, s[38:39]
	v_add_f32_e32 v8, v12, v8
	v_add_f32_e32 v9, v13, v9
	v_add_f32_e32 v10, v14, v10
	v_add_f32_e32 v27, v27, v28
	v_cndmask_b32_e64 v23, 0, v23, s[36:37]
	v_and_b32_e32 v7, 0xffff0000, v7
	v_add_f32_e32 v23, v27, v23
	v_cndmask_b32_e32 v15, 0, v15, vcc
	v_cndmask_b32_e32 v7, 0, v7, vcc
	v_add_f32_e32 v15, v23, v15
	s_waitcnt vmcnt(0)
	v_and_b32_e32 v12, 0xffff0000, v16
	v_lshlrev_b32_e32 v13, 16, v17
	v_and_b32_e32 v14, 0xffff0000, v17
	v_fma_f32 v12, v44, v4, -v12
	v_fma_f32 v8, v44, v8, -v13
	v_fma_f32 v13, v44, v5, -v14
	v_lshlrev_b64 v[4:5], 11, v[40:41]
	v_lshl_add_u64 v[4:5], s[8:9], 0, v[4:5]
	v_add_f32_e32 v7, v11, v7
	v_lshlrev_b32_e32 v11, 16, v16
	v_lshlrev_b32_e32 v16, 16, v18
	v_and_b32_e32 v17, 0xffff0000, v18
	v_lshlrev_b32_e32 v18, 16, v19
	v_and_b32_e32 v19, 0xffff0000, v19
	v_lshl_add_u64 v[4:5], v[4:5], 0, v[184:185]
	s_mov_b64 s[0:1], 0
	s_nop 1
	v_fma_f32 v11, v44, v15, -v11
	v_fma_f32 v9, v44, v9, -v16
	v_fma_f32 v6, v44, v6, -v17
	v_fma_f32 v10, v44, v10, -v18
	v_fma_f32 v7, v44, v7, -v19
	global_store_dwordx4 v[4:5], v[0:3], off offset:512
	s_nop 1
	v_cvt_pk_bf16_f32 v0, v11, v12
	v_cvt_pk_bf16_f32 v1, v8, v13
	v_cvt_pk_bf16_f32 v2, v9, v6
	v_cvt_pk_bf16_f32 v3, v10, v7
	global_store_dwordx4 v[4:5], v[0:3], off offset:1536
